# stage-1 half-sum pass unrolled: all 12 loads of a thread in flight before the adds and stores
# speedup vs baseline: 1.0098x; 1.0024x over previous
; __device__ __forceinline__ int tid_opaque() { int t = threadIdx.x; asm volatile("" : "+v"(t)); return t; }
; __device__ __forceinline__ unsigned pk2(float lo, float hi) { unsigned r; asm("v_cvt_pk_bf16_f32 %0, %1, %2" : "=v"(r) : "v"(lo), "v"(hi)); return r; }
; __global__ void __launch_bounds__(512, 2) fwd_megakernel(Params p) {
;     ...
;         if (stage == 1) {
;             const int tid = tid_opaque();
;             for (int i = bid * 512 + tid; i < 1536 * DM / 8; i += 256 * 512) {
;                 const f32x4 a0 = *(const f32x4*)(Fh + (size_t)i * 8), a1 = *(const f32x4*)(Fh + (size_t)i * 8 + 4), b0 = *(const f32x4*)(Fh + (size_t)1536 * DM + (size_t)i * 8), b1 = *(const f32x4*)(Fh + (size_t)1536 * DM + (size_t)i * 8 + 4);
;                 u32x4 w; w.x = pk2(a0[0] + b0[0], a0[1] + b0[1]); w.y = pk2(a0[2] + b0[2], a0[3] + b0[3]); w.z = pk2(a1[0] + b1[0], a1[1] + b1[1]); w.w = pk2(a1[2] + b1[2], a1[3] + b1[3]);
;                 *(u32x4*)(XN + (size_t)8192 * DM + (size_t)i * 8) = w; }
;             xcd_barrier(xb);
.LBB0_965:
	s_mov_b64 s[2:3], 0xc00000
	v_lshl_add_u64 v[6:7], v[2:3], 0, s[2:3]
	s_mov_b64 s[2:3], 0x400000
	v_lshl_add_u64 v[8:9], v[2:3], 0, s[2:3]
	v_lshl_add_u64 v[10:11], v[6:7], 0, s[2:3]
	v_lshl_add_u64 v[12:13], v[8:9], 0, s[2:3]
	v_lshl_add_u64 v[14:15], v[10:11], 0, s[2:3]
	global_load_dwordx4 v[16:19], v[2:3], off
	global_load_dwordx4 v[20:23], v[2:3], off offset:16
	global_load_dwordx4 v[24:27], v[6:7], off
	global_load_dwordx4 v[28:31], v[6:7], off offset:16
	global_load_dwordx4 v[32:35], v[8:9], off
	global_load_dwordx4 v[36:39], v[8:9], off offset:16
	global_load_dwordx4 v[40:43], v[10:11], off
	global_load_dwordx4 v[44:47], v[10:11], off offset:16
	global_load_dwordx4 v[48:51], v[12:13], off
	global_load_dwordx4 v[52:55], v[12:13], off offset:16
	global_load_dwordx4 v[56:59], v[14:15], off
	global_load_dwordx4 v[60:63], v[14:15], off offset:16
	s_mov_b64 s[2:3], 0x200000
	v_lshl_add_u64 v[64:65], v[4:5], 0, s[2:3]
	v_lshl_add_u64 v[66:67], v[64:65], 0, s[2:3]
	s_waitcnt vmcnt(8)
	v_add_f32_e32 v16, v16, v24
	v_add_f32_e32 v17, v17, v25
	v_add_f32_e32 v18, v18, v26
	v_add_f32_e32 v19, v19, v27
	v_add_f32_e32 v20, v20, v28
	v_add_f32_e32 v21, v21, v29
	v_add_f32_e32 v22, v22, v30
	v_add_f32_e32 v23, v23, v31
	v_cvt_pk_bf16_f32 v68, v16, v17
	v_cvt_pk_bf16_f32 v69, v18, v19
	v_cvt_pk_bf16_f32 v70, v20, v21
	v_cvt_pk_bf16_f32 v71, v22, v23
	global_store_dwordx4 v[4:5], v[68:71], off
	s_waitcnt vmcnt(5)
	v_add_f32_e32 v32, v32, v40
	v_add_f32_e32 v33, v33, v41
	v_add_f32_e32 v34, v34, v42
	v_add_f32_e32 v35, v35, v43
	v_add_f32_e32 v36, v36, v44
	v_add_f32_e32 v37, v37, v45
	v_add_f32_e32 v38, v38, v46
	v_add_f32_e32 v39, v39, v47
	v_cvt_pk_bf16_f32 v72, v32, v33
	v_cvt_pk_bf16_f32 v73, v34, v35
	v_cvt_pk_bf16_f32 v74, v36, v37
	v_cvt_pk_bf16_f32 v75, v38, v39
	global_store_dwordx4 v[64:65], v[72:75], off
	s_waitcnt vmcnt(2)
	v_add_f32_e32 v48, v48, v56
	v_add_f32_e32 v49, v49, v57
	v_add_f32_e32 v50, v50, v58
	v_add_f32_e32 v51, v51, v59
	v_add_f32_e32 v52, v52, v60
	v_add_f32_e32 v53, v53, v61
	v_add_f32_e32 v54, v54, v62
	v_add_f32_e32 v55, v55, v63
	v_cvt_pk_bf16_f32 v76, v48, v49
	v_cvt_pk_bf16_f32 v77, v50, v51
	v_cvt_pk_bf16_f32 v78, v52, v53
	v_cvt_pk_bf16_f32 v79, v54, v55
	global_store_dwordx4 v[66:67], v[76:79], off
